# sc1 write-through on the 16 FF1 (phase 8) epilogue stores
# speedup vs baseline: 1.0001x; 1.0001x over previous
.LBB0_880:
	v_lshl_add_u32 v150, s34, 8, v144
	v_max_f32_e32 v124, v124, v124
	v_max_f32_e32 v120, v120, v120
	v_max_f32_e32 v125, v125, v125
	v_max_f32_e32 v121, v121, v121
	v_max_f32_e32 v126, v126, v126
	v_max_f32_e32 v127, v127, v127
	v_lshl_or_b32 v152, s56, 8, v146
	v_ashrrev_i32_e32 v151, 31, v150
	v_max_f32_e32 v124, 0, v124
	v_max_f32_e32 v120, 0, v120
	v_max_f32_e32 v125, 0, v125
	v_max_f32_e32 v121, 0, v121
	v_max_f32_e32 v126, 0, v126
	v_max_f32_e32 v122, v122, v122
	v_max_f32_e32 v127, 0, v127
	v_max_f32_e32 v123, v123, v123
	v_ashrrev_i32_e32 v153, 31, v152
	v_lshlrev_b64 v[154:155], 13, v[150:151]
	v_pk_mul_f32 v[124:125], v[124:125], v[124:125]
	v_pk_mul_f32 v[120:121], v[120:121], v[120:121]
	v_max_f32_e32 v122, 0, v122
	v_max_f32_e32 v123, 0, v123
	v_pk_mul_f32 v[126:127], v[126:127], v[126:127]
	v_pk_mul_f32 v[156:157], v[122:123], v[122:123]
	v_cvt_pk_bf16_f32 v122, v124, v125
	v_cvt_pk_bf16_f32 v123, v126, v127
	v_cvt_pk_bf16_f32 v124, v120, v121
	v_lshl_add_u64 v[120:121], s[78:79], 0, v[154:155]
	v_lshlrev_b64 v[126:127], 1, v[152:153]
	v_max_f32_e32 v112, v112, v112
	v_max_f32_e32 v113, v113, v113
	v_cvt_pk_bf16_f32 v125, v156, v157
	v_lshl_add_u64 v[120:121], v[120:121], 0, v[126:127]
	v_max_f32_e32 v112, 0, v112
	v_max_f32_e32 v113, 0, v113
	global_store_dwordx4 v[120:121], v[122:125], off sc1
	v_max_f32_e32 v116, v116, v116
	v_max_f32_e32 v117, v117, v117
	v_pk_mul_f32 v[122:123], v[112:113], v[112:113]
	v_max_f32_e32 v113, v114, v114
	v_max_f32_e32 v112, v118, v118
	v_max_f32_e32 v114, 0, v113
	v_max_f32_e32 v113, v119, v119
	v_max_f32_e32 v115, v115, v115
	v_max_f32_e32 v116, 0, v116
	v_max_f32_e32 v117, 0, v117
	v_max_f32_e32 v112, 0, v112
	v_max_f32_e32 v113, 0, v113
	v_max_f32_e32 v115, 0, v115
	v_pk_mul_f32 v[116:117], v[116:117], v[116:117]
	v_pk_mul_f32 v[118:119], v[112:113], v[112:113]
	v_pk_mul_f32 v[124:125], v[114:115], v[114:115]
	v_max_f32_e32 v104, v104, v104
	v_max_f32_e32 v105, v105, v105
	v_cvt_pk_bf16_f32 v112, v116, v117
	v_cvt_pk_bf16_f32 v113, v118, v119
	v_cvt_pk_bf16_f32 v114, v122, v123
	v_cvt_pk_bf16_f32 v115, v124, v125
	v_max_f32_e32 v104, 0, v104
	v_max_f32_e32 v105, 0, v105
	global_store_dwordx4 v[120:121], v[112:115], off offset:256 sc1
	v_max_f32_e32 v108, v108, v108
	v_max_f32_e32 v109, v109, v109
	v_or_b32_e32 v112, 16, v150
	v_pk_mul_f32 v[114:115], v[104:105], v[104:105]
	v_max_f32_e32 v105, v106, v106
	v_ashrrev_i32_e32 v113, 31, v112
	v_max_f32_e32 v108, 0, v108
	v_max_f32_e32 v109, 0, v109
	v_max_f32_e32 v104, v110, v110
	v_max_f32_e32 v106, 0, v105
	v_max_f32_e32 v105, v111, v111
	v_max_f32_e32 v107, v107, v107
	v_lshlrev_b64 v[112:113], 13, v[112:113]
	v_pk_mul_f32 v[108:109], v[108:109], v[108:109]
	v_max_f32_e32 v104, 0, v104
	v_max_f32_e32 v105, 0, v105
	v_max_f32_e32 v107, 0, v107
	v_pk_mul_f32 v[110:111], v[104:105], v[104:105]
	v_pk_mul_f32 v[116:117], v[106:107], v[106:107]
	v_cvt_pk_bf16_f32 v104, v108, v109
	v_lshl_add_u64 v[108:109], s[78:79], 0, v[112:113]
	v_max_f32_e32 v96, v96, v96
	v_max_f32_e32 v97, v97, v97
	v_cvt_pk_bf16_f32 v105, v110, v111
	v_cvt_pk_bf16_f32 v106, v114, v115
	v_cvt_pk_bf16_f32 v107, v116, v117
	v_lshl_add_u64 v[108:109], v[108:109], 0, v[126:127]
	v_max_f32_e32 v96, 0, v96
	v_max_f32_e32 v97, 0, v97
	global_store_dwordx4 v[108:109], v[104:107], off sc1
	v_max_f32_e32 v100, v100, v100
	v_max_f32_e32 v101, v101, v101
	v_pk_mul_f32 v[104:105], v[96:97], v[96:97]
	v_max_f32_e32 v97, v98, v98
	v_max_f32_e32 v96, v102, v102
	v_max_f32_e32 v98, 0, v97
	v_max_f32_e32 v97, v103, v103
	v_max_f32_e32 v99, v99, v99
	v_max_f32_e32 v100, 0, v100
	v_max_f32_e32 v101, 0, v101
	v_max_f32_e32 v96, 0, v96
	v_max_f32_e32 v97, 0, v97
	v_max_f32_e32 v99, 0, v99
	v_pk_mul_f32 v[100:101], v[100:101], v[100:101]
	v_pk_mul_f32 v[102:103], v[96:97], v[96:97]
	v_pk_mul_f32 v[106:107], v[98:99], v[98:99]
	v_max_f32_e32 v88, v88, v88
	v_max_f32_e32 v89, v89, v89
	v_cvt_pk_bf16_f32 v96, v100, v101
	v_cvt_pk_bf16_f32 v97, v102, v103
	v_cvt_pk_bf16_f32 v98, v104, v105
	v_cvt_pk_bf16_f32 v99, v106, v107
	v_max_f32_e32 v88, 0, v88
	v_max_f32_e32 v89, 0, v89
	global_store_dwordx4 v[108:109], v[96:99], off offset:256 sc1
	v_max_f32_e32 v92, v92, v92
	v_max_f32_e32 v93, v93, v93
	v_or_b32_e32 v96, 32, v150
	v_pk_mul_f32 v[98:99], v[88:89], v[88:89]
	v_max_f32_e32 v89, v90, v90
	v_ashrrev_i32_e32 v97, 31, v96
	v_max_f32_e32 v92, 0, v92
	v_max_f32_e32 v93, 0, v93
	v_max_f32_e32 v88, v94, v94
	v_max_f32_e32 v90, 0, v89
	v_max_f32_e32 v89, v95, v95
	v_max_f32_e32 v91, v91, v91
	v_lshlrev_b64 v[96:97], 13, v[96:97]
	v_pk_mul_f32 v[92:93], v[92:93], v[92:93]
	v_max_f32_e32 v88, 0, v88
	v_max_f32_e32 v89, 0, v89
	v_max_f32_e32 v91, 0, v91
	v_pk_mul_f32 v[94:95], v[88:89], v[88:89]
	v_pk_mul_f32 v[100:101], v[90:91], v[90:91]
	v_cvt_pk_bf16_f32 v88, v92, v93
	v_lshl_add_u64 v[92:93], s[78:79], 0, v[96:97]
	v_max_f32_e32 v80, v80, v80
	v_max_f32_e32 v81, v81, v81
	v_cvt_pk_bf16_f32 v89, v94, v95
	v_cvt_pk_bf16_f32 v90, v98, v99
	v_cvt_pk_bf16_f32 v91, v100, v101
	v_lshl_add_u64 v[92:93], v[92:93], 0, v[126:127]
	v_max_f32_e32 v80, 0, v80
	v_max_f32_e32 v81, 0, v81
	global_store_dwordx4 v[92:93], v[88:91], off sc1
	v_max_f32_e32 v84, v84, v84
	v_max_f32_e32 v85, v85, v85
	v_pk_mul_f32 v[88:89], v[80:81], v[80:81]
	v_max_f32_e32 v81, v82, v82
	v_max_f32_e32 v80, v86, v86
	v_max_f32_e32 v82, 0, v81
	v_max_f32_e32 v81, v87, v87
	v_max_f32_e32 v83, v83, v83
	v_max_f32_e32 v84, 0, v84
	v_max_f32_e32 v85, 0, v85
	v_max_f32_e32 v80, 0, v80
	v_max_f32_e32 v81, 0, v81
	v_max_f32_e32 v83, 0, v83
	v_pk_mul_f32 v[84:85], v[84:85], v[84:85]
	v_pk_mul_f32 v[86:87], v[80:81], v[80:81]
	v_pk_mul_f32 v[90:91], v[82:83], v[82:83]
	v_max_f32_e32 v72, v72, v72
	v_max_f32_e32 v73, v73, v73
	v_cvt_pk_bf16_f32 v80, v84, v85
	v_cvt_pk_bf16_f32 v81, v86, v87
	v_cvt_pk_bf16_f32 v82, v88, v89
	v_cvt_pk_bf16_f32 v83, v90, v91
	v_max_f32_e32 v72, 0, v72
	v_max_f32_e32 v73, 0, v73
	global_store_dwordx4 v[92:93], v[80:83], off offset:256 sc1
	v_max_f32_e32 v76, v76, v76
	v_max_f32_e32 v77, v77, v77
	v_or_b32_e32 v80, 48, v150
	v_pk_mul_f32 v[82:83], v[72:73], v[72:73]
	v_max_f32_e32 v73, v74, v74
	v_ashrrev_i32_e32 v81, 31, v80
	v_max_f32_e32 v76, 0, v76
	v_max_f32_e32 v77, 0, v77
	v_max_f32_e32 v72, v78, v78
	v_max_f32_e32 v74, 0, v73
	v_max_f32_e32 v73, v79, v79
	v_max_f32_e32 v75, v75, v75
	v_lshlrev_b64 v[80:81], 13, v[80:81]
	v_pk_mul_f32 v[76:77], v[76:77], v[76:77]
	v_max_f32_e32 v72, 0, v72
	v_max_f32_e32 v73, 0, v73
	v_max_f32_e32 v75, 0, v75
	v_pk_mul_f32 v[78:79], v[72:73], v[72:73]
	v_pk_mul_f32 v[84:85], v[74:75], v[74:75]
	v_cvt_pk_bf16_f32 v72, v76, v77
	v_lshl_add_u64 v[76:77], s[78:79], 0, v[80:81]
	v_max_f32_e32 v64, v64, v64
	v_max_f32_e32 v65, v65, v65
	v_cvt_pk_bf16_f32 v73, v78, v79
	v_cvt_pk_bf16_f32 v74, v82, v83
	v_cvt_pk_bf16_f32 v75, v84, v85
	v_lshl_add_u64 v[76:77], v[76:77], 0, v[126:127]
	v_max_f32_e32 v64, 0, v64
	v_max_f32_e32 v65, 0, v65
	global_store_dwordx4 v[76:77], v[72:75], off sc1
	v_max_f32_e32 v68, v68, v68
	v_max_f32_e32 v69, v69, v69
	v_pk_mul_f32 v[72:73], v[64:65], v[64:65]
	v_max_f32_e32 v65, v66, v66
	v_max_f32_e32 v64, v70, v70
	v_max_f32_e32 v66, 0, v65
	v_max_f32_e32 v65, v71, v71
	v_max_f32_e32 v67, v67, v67
	v_max_f32_e32 v68, 0, v68
	v_max_f32_e32 v69, 0, v69
	v_max_f32_e32 v64, 0, v64
	v_max_f32_e32 v65, 0, v65
	v_max_f32_e32 v67, 0, v67
	v_pk_mul_f32 v[68:69], v[68:69], v[68:69]
	v_pk_mul_f32 v[70:71], v[64:65], v[64:65]
	v_pk_mul_f32 v[74:75], v[66:67], v[66:67]
	v_max_f32_e32 v56, v56, v56
	v_max_f32_e32 v57, v57, v57
	v_cvt_pk_bf16_f32 v64, v68, v69
	v_cvt_pk_bf16_f32 v65, v70, v71
	v_cvt_pk_bf16_f32 v66, v72, v73
	v_cvt_pk_bf16_f32 v67, v74, v75
	v_max_f32_e32 v56, 0, v56
	v_max_f32_e32 v57, 0, v57
	global_store_dwordx4 v[76:77], v[64:67], off offset:256 sc1
	v_max_f32_e32 v60, v60, v60
	v_max_f32_e32 v61, v61, v61
	v_pk_mul_f32 v[64:65], v[56:57], v[56:57]
	v_max_f32_e32 v57, v58, v58
	v_max_f32_e32 v56, v62, v62
	v_max_f32_e32 v58, 0, v57
	v_max_f32_e32 v57, v63, v63
	v_max_f32_e32 v56, 0, v56
	v_max_f32_e32 v57, 0, v57
	v_max_f32_e32 v59, v59, v59
	v_max_f32_e32 v60, 0, v60
	v_max_f32_e32 v61, 0, v61
	v_max_f32_e32 v59, 0, v59
	v_pk_mul_f32 v[62:63], v[56:57], v[56:57]
	v_pk_mul_f32 v[60:61], v[60:61], v[60:61]
	v_pk_mul_f32 v[66:67], v[58:59], v[58:59]
	v_cvt_pk_bf16_f32 v57, v62, v63
	v_add_co_u32_e32 v62, vcc, s52, v120
	v_max_f32_e32 v48, v48, v48
	v_max_f32_e32 v49, v49, v49
	v_cvt_pk_bf16_f32 v56, v60, v61
	v_cvt_pk_bf16_f32 v58, v64, v65
	v_cvt_pk_bf16_f32 v59, v66, v67
	v_addc_co_u32_e32 v63, vcc, 0, v121, vcc
	v_max_f32_e32 v48, 0, v48
	v_max_f32_e32 v49, 0, v49
	global_store_dwordx4 v[62:63], v[56:59], off sc1
	v_max_f32_e32 v52, v52, v52
	v_max_f32_e32 v53, v53, v53
	v_pk_mul_f32 v[56:57], v[48:49], v[48:49]
	v_max_f32_e32 v49, v50, v50
	v_max_f32_e32 v48, v54, v54
	v_max_f32_e32 v50, 0, v49
	v_max_f32_e32 v49, v55, v55
	v_max_f32_e32 v51, v51, v51
	v_max_f32_e32 v52, 0, v52
	v_max_f32_e32 v53, 0, v53
	v_max_f32_e32 v48, 0, v48
	v_max_f32_e32 v49, 0, v49
	v_max_f32_e32 v51, 0, v51
	v_pk_mul_f32 v[52:53], v[52:53], v[52:53]
	v_pk_mul_f32 v[54:55], v[48:49], v[48:49]
	v_pk_mul_f32 v[58:59], v[50:51], v[50:51]
	v_max_f32_e32 v40, v40, v40
	v_max_f32_e32 v41, v41, v41
	v_lshl_add_u64 v[60:61], v[120:121], 0, s[16:17]
	v_cvt_pk_bf16_f32 v48, v52, v53
	v_cvt_pk_bf16_f32 v49, v54, v55
	v_cvt_pk_bf16_f32 v50, v56, v57
	v_cvt_pk_bf16_f32 v51, v58, v59
	v_max_f32_e32 v40, 0, v40
	v_max_f32_e32 v41, 0, v41
	global_store_dwordx4 v[60:61], v[48:51], off offset:256 sc1
	v_max_f32_e32 v44, v44, v44
	v_max_f32_e32 v45, v45, v45
	v_pk_mul_f32 v[48:49], v[40:41], v[40:41]
	v_max_f32_e32 v41, v42, v42
	v_max_f32_e32 v40, v46, v46
	v_max_f32_e32 v42, 0, v41
	v_max_f32_e32 v41, v47, v47
	v_max_f32_e32 v40, 0, v40
	v_max_f32_e32 v41, 0, v41
	v_max_f32_e32 v43, v43, v43
	v_max_f32_e32 v44, 0, v44
	v_max_f32_e32 v45, 0, v45
	v_max_f32_e32 v43, 0, v43
	v_pk_mul_f32 v[46:47], v[40:41], v[40:41]
	v_pk_mul_f32 v[44:45], v[44:45], v[44:45]
	v_pk_mul_f32 v[50:51], v[42:43], v[42:43]
	v_cvt_pk_bf16_f32 v41, v46, v47
	v_add_co_u32_e32 v46, vcc, s53, v120
	v_max_f32_e32 v32, v32, v32
	v_max_f32_e32 v33, v33, v33
	v_cvt_pk_bf16_f32 v40, v44, v45
	v_cvt_pk_bf16_f32 v42, v48, v49
	v_cvt_pk_bf16_f32 v43, v50, v51
	v_addc_co_u32_e32 v47, vcc, 0, v121, vcc
	v_max_f32_e32 v32, 0, v32
	v_max_f32_e32 v33, 0, v33
	global_store_dwordx4 v[46:47], v[40:43], off sc1
	v_max_f32_e32 v36, v36, v36
	v_max_f32_e32 v37, v37, v37
	v_pk_mul_f32 v[40:41], v[32:33], v[32:33]
	v_max_f32_e32 v33, v34, v34
	v_max_f32_e32 v32, v38, v38
	v_max_f32_e32 v34, 0, v33
	v_max_f32_e32 v33, v39, v39
	v_max_f32_e32 v35, v35, v35
	v_max_f32_e32 v36, 0, v36
	v_max_f32_e32 v37, 0, v37
	v_max_f32_e32 v32, 0, v32
	v_max_f32_e32 v33, 0, v33
	v_max_f32_e32 v35, 0, v35
	v_pk_mul_f32 v[36:37], v[36:37], v[36:37]
	v_pk_mul_f32 v[38:39], v[32:33], v[32:33]
	v_pk_mul_f32 v[42:43], v[34:35], v[34:35]
	v_max_f32_e32 v24, v24, v24
	v_max_f32_e32 v25, v25, v25
	v_lshl_add_u64 v[44:45], v[120:121], 0, s[18:19]
	v_cvt_pk_bf16_f32 v32, v36, v37
	v_cvt_pk_bf16_f32 v33, v38, v39
	v_cvt_pk_bf16_f32 v34, v40, v41
	v_cvt_pk_bf16_f32 v35, v42, v43
	v_max_f32_e32 v24, 0, v24
	v_max_f32_e32 v25, 0, v25
	global_store_dwordx4 v[44:45], v[32:35], off offset:256 sc1
	v_max_f32_e32 v28, v28, v28
	v_max_f32_e32 v29, v29, v29
	v_pk_mul_f32 v[32:33], v[24:25], v[24:25]
	v_max_f32_e32 v25, v26, v26
	v_max_f32_e32 v24, v30, v30
	v_max_f32_e32 v26, 0, v25
	v_max_f32_e32 v25, v31, v31
	v_max_f32_e32 v24, 0, v24
	v_max_f32_e32 v25, 0, v25
	v_max_f32_e32 v27, v27, v27
	v_max_f32_e32 v28, 0, v28
	v_max_f32_e32 v29, 0, v29
	v_max_f32_e32 v27, 0, v27
	v_pk_mul_f32 v[30:31], v[24:25], v[24:25]
	v_pk_mul_f32 v[28:29], v[28:29], v[28:29]
	v_pk_mul_f32 v[34:35], v[26:27], v[26:27]
	v_cvt_pk_bf16_f32 v25, v30, v31
	v_add_co_u32_e32 v30, vcc, s54, v120
	v_max_f32_e32 v16, v16, v16
	v_max_f32_e32 v17, v17, v17
	v_cvt_pk_bf16_f32 v24, v28, v29
	v_cvt_pk_bf16_f32 v26, v32, v33
	v_cvt_pk_bf16_f32 v27, v34, v35
	v_addc_co_u32_e32 v31, vcc, 0, v121, vcc
	v_max_f32_e32 v16, 0, v16
	v_max_f32_e32 v17, 0, v17
	global_store_dwordx4 v[30:31], v[24:27], off sc1
	v_max_f32_e32 v20, v20, v20
	v_max_f32_e32 v21, v21, v21
	v_pk_mul_f32 v[24:25], v[16:17], v[16:17]
	v_max_f32_e32 v17, v18, v18
	v_max_f32_e32 v16, v22, v22
	v_max_f32_e32 v18, 0, v17
	v_max_f32_e32 v17, v23, v23
	v_max_f32_e32 v19, v19, v19
	v_max_f32_e32 v20, 0, v20
	v_max_f32_e32 v21, 0, v21
	v_max_f32_e32 v16, 0, v16
	v_max_f32_e32 v17, 0, v17
	v_max_f32_e32 v19, 0, v19
	v_pk_mul_f32 v[20:21], v[20:21], v[20:21]
	v_pk_mul_f32 v[22:23], v[16:17], v[16:17]
	v_pk_mul_f32 v[26:27], v[18:19], v[18:19]
	v_max_f32_e32 v8, v8, v8
	v_max_f32_e32 v9, v9, v9
	v_lshl_add_u64 v[28:29], v[120:121], 0, s[20:21]
	v_cvt_pk_bf16_f32 v16, v20, v21
	v_cvt_pk_bf16_f32 v17, v22, v23
	v_cvt_pk_bf16_f32 v18, v24, v25
	v_cvt_pk_bf16_f32 v19, v26, v27
	v_max_f32_e32 v8, 0, v8
	v_max_f32_e32 v9, 0, v9
	global_store_dwordx4 v[28:29], v[16:19], off offset:256 sc1
	v_max_f32_e32 v12, v12, v12
	v_max_f32_e32 v13, v13, v13
	v_pk_mul_f32 v[16:17], v[8:9], v[8:9]
	v_max_f32_e32 v9, v10, v10
	v_max_f32_e32 v8, v14, v14
	v_max_f32_e32 v10, 0, v9
	v_max_f32_e32 v9, v15, v15
	v_max_f32_e32 v8, 0, v8
	v_max_f32_e32 v9, 0, v9
	v_max_f32_e32 v11, v11, v11
	v_max_f32_e32 v12, 0, v12
	v_max_f32_e32 v13, 0, v13
	v_max_f32_e32 v11, 0, v11
	v_pk_mul_f32 v[14:15], v[8:9], v[8:9]
	v_pk_mul_f32 v[12:13], v[12:13], v[12:13]
	v_pk_mul_f32 v[18:19], v[10:11], v[10:11]
	v_cvt_pk_bf16_f32 v9, v14, v15
	v_add_co_u32_e32 v14, vcc, s55, v120
	v_max_f32_e32 v0, v0, v0
	v_max_f32_e32 v1, v1, v1
	v_cvt_pk_bf16_f32 v8, v12, v13
	v_cvt_pk_bf16_f32 v10, v16, v17
	v_cvt_pk_bf16_f32 v11, v18, v19
	v_addc_co_u32_e32 v15, vcc, 0, v121, vcc
	v_max_f32_e32 v0, 0, v0
	v_max_f32_e32 v1, 0, v1
	global_store_dwordx4 v[14:15], v[8:11], off sc1
	v_max_f32_e32 v4, v4, v4
	v_max_f32_e32 v5, v5, v5
	v_pk_mul_f32 v[8:9], v[0:1], v[0:1]
	v_max_f32_e32 v1, v2, v2
	v_max_f32_e32 v0, v6, v6
	v_max_f32_e32 v2, 0, v1
	v_max_f32_e32 v1, v7, v7
	v_max_f32_e32 v3, v3, v3
	v_max_f32_e32 v4, 0, v4
	v_max_f32_e32 v5, 0, v5
	v_max_f32_e32 v0, 0, v0
	v_max_f32_e32 v1, 0, v1
	v_max_f32_e32 v3, 0, v3
	v_pk_mul_f32 v[4:5], v[4:5], v[4:5]
	v_pk_mul_f32 v[6:7], v[0:1], v[0:1]
	v_pk_mul_f32 v[10:11], v[2:3], v[2:3]
	v_lshl_add_u64 v[12:13], v[120:121], 0, s[22:23]
	v_cvt_pk_bf16_f32 v0, v4, v5
	v_cvt_pk_bf16_f32 v1, v6, v7
	v_cvt_pk_bf16_f32 v2, v8, v9
	v_cvt_pk_bf16_f32 v3, v10, v11
	s_andn2_b64 vcc, exec, s[4:5]
	s_mov_b64 s[4:5], -1
	global_store_dwordx4 v[12:13], v[0:3], off offset:256 sc1
	s_cbranch_vccnz .LBB0_869
	s_andn2_b64 vcc, exec, s[6:7]
	s_cbranch_vccnz .LBB0_868
	s_barrier
	s_branch .LBB0_868
